# also the P6 residual epilogue de-serialised the same way (gate once, residual loads 8 deep)
# speedup vs baseline: 1.0035x; 1.0035x over previous
; #define LAUNDER_GPTR(p) do { p = launder_gptr(p); } while (0)
;     __device__ __forceinline__ void operator()(const f32x4 (&acc)[2][2][4][2], const Unit& u, int wr, int wc, int fr, int fq) const {
;         unsigned char* ws = P->ws; LAUNDER_GPTR(ws);
;         const float* MOD = (const float*)(ws + WS_MOD);
;         float* X1 = (float*)(ws + WS_X1);
;         const int col0 = u.pn * 256 + wc * 32 + 8 * fq;
; #pragma unroll
;         for (int ai = 0; ai < 2; ++ai)
; #pragma unroll
;             for (int m = 0; m < 4; ++m) {
;                 const int r = u.pm * 256 + ai * 128 + wr * 64 + m * 16 + fr;
;                 const float* gate = MOD + (size_t)mod_row(r) * 6144 + (WHICH == 0 ? 2048 : 5120) + col0;
;                 const float* res = (WHICH == 0) ? (r < NPR ? P->in[0] + (size_t)r * DM : P->in[1] + (size_t)(r - NPR) * DM) + col0 : X1 + (size_t)r * DM + col0;
;                 float* dst = (WHICH == 0) ? X1 + (size_t)r * DM + col0 : P->out + (size_t)r * DM + col0;
; #pragma unroll
;                 for (int bj = 0; bj < 2; ++bj)
; #pragma unroll
;                     for (int n = 0; n < 2; ++n) { const int o = bj * 128 + 4 * n;
;                         const f32x4 g = *(const f32x4*)(gate + o), x = *(const f32x4*)(res + o);
;                         *(f32x4*)(dst + o) = x + g * acc[ai][bj][m][n]; }
;             }
;     }
.LBB0_1679:
	s_lshl_b32 s27, s6, 8
	s_add_i32 s27, s27, s52
	v_or_b32_e32 v150, s27, v154
	s_mov_b64 s[38:39], s[14:15]
	v_cmp_gt_i32_e32 vcc, s50, v150
	v_cmp_lt_i32_e64 s[6:7], s59, v150
	v_add_u32_e32 v136, 0xffffc000, v150
	s_and_saveexec_b64 s[40:41], s[6:7]
	s_xor_b64 s[6:7], exec, s[40:41]
	v_lshlrev_b64 v[146:147], 12, v[136:137]
	v_mov_b32_e32 v151, v137
	v_lshl_add_u64 v[148:149], s[10:11], 0, v[146:147]
	v_lshlrev_b64 v[152:153], 12, v[150:151]
	s_andn2_saveexec_b64 s[6:7], s[6:7]
	v_ashrrev_i32_e32 v151, 31, v150
	v_lshlrev_b64 v[152:153], 12, v[150:151]
	v_lshl_add_u64 v[148:149], s[8:9], 0, v[152:153]
	s_or_b64 exec, exec, s[6:7]
	s_ashr_i32 s29, s27, 13
	v_lshrrev_b32_e32 v136, 2, v136
	v_lshl_or_b32 v146, s36, 8, v156
	v_add_u32_e32 v136, 2, v136
	v_mov_b32_e32 v151, s29
	v_ashrrev_i32_e32 v147, 31, v146
	v_cndmask_b32_e32 v136, v136, v151, vcc
	v_mov_b64_e32 v[160:161], s[38:39]
	v_lshlrev_b64 v[146:147], 2, v[146:147]
	v_mad_i64_i32 v[160:161], s[6:7], v136, s51, v[160:161]
	v_lshl_add_u64 v[168:169], v[160:161], 0, v[146:147]
	v_lshl_add_u64 v[170:171], v[148:149], 0, v[146:147]
	v_add_co_u32_e32 v148, vcc, s60, v168
	v_add_u32_e32 v136, 0xffffc010, v150
	s_nop 0
	v_addc_co_u32_e32 v149, vcc, 0, v169, vcc
	v_lshl_add_u64 v[148:149], s[38:39], 0, v[146:147]
	v_lshl_add_u64 v[148:149], v[148:149], 0, s[22:23]
	v_lshl_add_u64 v[152:153], v[148:149], 0, v[152:153]
	v_lshl_add_u64 v[168:169], v[168:169], 0, s[24:25]
	v_readfirstlane_b32 s98, v170
	v_readfirstlane_b32 s99, v171
	v_readfirstlane_b32 s100, v152
	v_readfirstlane_b32 s101, v153
	global_load_dwordx4 v[172:175], v[168:169], off offset:0
	global_load_dwordx4 v[176:179], v[168:169], off offset:16
	global_load_dwordx4 v[180:183], v[168:169], off offset:512
	global_load_dwordx4 v[184:187], v[168:169], off offset:528
	v_subrev_u32_e32 v146, s98, v170
	v_add_u32_e32 v147, 0x10000, v146
	v_add_u32_e32 v148, 0x20000, v146
	v_add_u32_e32 v149, 0x30000, v146
	v_add_u32_e32 v150, 0x80000, v146
	v_add_u32_e32 v151, 0x90000, v146
	v_add_u32_e32 v164, 0xa0000, v146
	v_add_u32_e32 v165, 0xb0000, v146
	global_load_dwordx4 v[188:191], v146, s[98:99] offset:0
	global_load_dwordx4 v[192:195], v146, s[98:99] offset:16
	global_load_dwordx4 v[196:199], v146, s[98:99] offset:512
	global_load_dwordx4 v[200:203], v146, s[98:99] offset:528
	global_load_dwordx4 v[204:207], v147, s[98:99] offset:0
	global_load_dwordx4 v[208:211], v147, s[98:99] offset:16
	global_load_dwordx4 v[212:215], v147, s[98:99] offset:512
	global_load_dwordx4 v[160:163], v147, s[98:99] offset:528
	s_waitcnt vmcnt(7)
	v_pk_fma_f32 v[124:125], v[124:125], v[172:173], v[188:189]
	v_pk_fma_f32 v[126:127], v[126:127], v[174:175], v[190:191]
	global_store_dwordx4 v146, v[124:127], s[100:101] offset:0
	global_load_dwordx4 v[188:191], v148, s[98:99] offset:0
	s_waitcnt vmcnt(8)
	v_pk_fma_f32 v[120:121], v[120:121], v[176:177], v[192:193]
	v_pk_fma_f32 v[122:123], v[122:123], v[178:179], v[194:195]
	global_store_dwordx4 v146, v[120:123], s[100:101] offset:16
	global_load_dwordx4 v[192:195], v148, s[98:99] offset:16
	s_waitcnt vmcnt(9)
	v_pk_fma_f32 v[116:117], v[116:117], v[180:181], v[196:197]
	v_pk_fma_f32 v[118:119], v[118:119], v[182:183], v[198:199]
	global_store_dwordx4 v146, v[116:119], s[100:101] offset:512
	global_load_dwordx4 v[196:199], v148, s[98:99] offset:512
	s_waitcnt vmcnt(10)
	v_pk_fma_f32 v[112:113], v[112:113], v[184:185], v[200:201]
	v_pk_fma_f32 v[114:115], v[114:115], v[186:187], v[202:203]
	global_store_dwordx4 v146, v[112:115], s[100:101] offset:528
	global_load_dwordx4 v[200:203], v148, s[98:99] offset:528
	s_waitcnt vmcnt(11)
	v_pk_fma_f32 v[108:109], v[108:109], v[172:173], v[204:205]
	v_pk_fma_f32 v[110:111], v[110:111], v[174:175], v[206:207]
	global_store_dwordx4 v147, v[108:111], s[100:101] offset:0
	global_load_dwordx4 v[204:207], v149, s[98:99] offset:0
	s_waitcnt vmcnt(12)
	v_pk_fma_f32 v[104:105], v[104:105], v[176:177], v[208:209]
	v_pk_fma_f32 v[106:107], v[106:107], v[178:179], v[210:211]
	global_store_dwordx4 v147, v[104:107], s[100:101] offset:16
	global_load_dwordx4 v[208:211], v149, s[98:99] offset:16
	s_waitcnt vmcnt(13)
	v_pk_fma_f32 v[100:101], v[100:101], v[180:181], v[212:213]
	v_pk_fma_f32 v[102:103], v[102:103], v[182:183], v[214:215]
	global_store_dwordx4 v147, v[100:103], s[100:101] offset:512
	global_load_dwordx4 v[212:215], v149, s[98:99] offset:512
	s_waitcnt vmcnt(14)
	v_pk_fma_f32 v[96:97], v[96:97], v[184:185], v[160:161]
	v_pk_fma_f32 v[98:99], v[98:99], v[186:187], v[162:163]
	global_store_dwordx4 v147, v[96:99], s[100:101] offset:528
	global_load_dwordx4 v[160:163], v149, s[98:99] offset:528
	s_waitcnt vmcnt(14)
	v_pk_fma_f32 v[92:93], v[92:93], v[172:173], v[188:189]
	v_pk_fma_f32 v[94:95], v[94:95], v[174:175], v[190:191]
	global_store_dwordx4 v148, v[92:95], s[100:101] offset:0
	global_load_dwordx4 v[188:191], v150, s[98:99] offset:0
	s_waitcnt vmcnt(14)
	v_pk_fma_f32 v[88:89], v[88:89], v[176:177], v[192:193]
	v_pk_fma_f32 v[90:91], v[90:91], v[178:179], v[194:195]
	global_store_dwordx4 v148, v[88:91], s[100:101] offset:16
	global_load_dwordx4 v[192:195], v150, s[98:99] offset:16
	s_waitcnt vmcnt(14)
;     __device__ __forceinline__ void operator()(const f32x4 (&acc)[2][2][4][2], const Unit& u, int wr, int wc, int fr, int fq) const {
;     ...
;                 const float* res = (WHICH == 0) ? (r < NPR ? P->in[0] + (size_t)r * DM : P->in[1] + (size_t)(r - NPR) * DM) + col0 : X1 + (size_t)r * DM + col0;
;                 float* dst = (WHICH == 0) ? X1 + (size_t)r * DM + col0 : P->out + (size_t)r * DM + col0;
; #pragma unroll
;                 for (int bj = 0; bj < 2; ++bj)
; #pragma unroll
;                     for (int n = 0; n < 2; ++n) { const int o = bj * 128 + 4 * n;
;                         const f32x4 g = *(const f32x4*)(gate + o), x = *(const f32x4*)(res + o);
;                         *(f32x4*)(dst + o) = x + g * acc[ai][bj][m][n]; }
	v_pk_fma_f32 v[84:85], v[84:85], v[180:181], v[196:197]
	v_pk_fma_f32 v[86:87], v[86:87], v[182:183], v[198:199]
	global_store_dwordx4 v148, v[84:87], s[100:101] offset:512
	global_load_dwordx4 v[196:199], v150, s[98:99] offset:512
	s_waitcnt vmcnt(14)
	v_pk_fma_f32 v[80:81], v[80:81], v[184:185], v[200:201]
	v_pk_fma_f32 v[82:83], v[82:83], v[186:187], v[202:203]
	global_store_dwordx4 v148, v[80:83], s[100:101] offset:528
	global_load_dwordx4 v[200:203], v150, s[98:99] offset:528
	s_waitcnt vmcnt(14)
	v_pk_fma_f32 v[76:77], v[76:77], v[172:173], v[204:205]
	v_pk_fma_f32 v[78:79], v[78:79], v[174:175], v[206:207]
	global_store_dwordx4 v149, v[76:79], s[100:101] offset:0
	global_load_dwordx4 v[204:207], v151, s[98:99] offset:0
	s_waitcnt vmcnt(14)
	v_pk_fma_f32 v[72:73], v[72:73], v[176:177], v[208:209]
	v_pk_fma_f32 v[74:75], v[74:75], v[178:179], v[210:211]
	global_store_dwordx4 v149, v[72:75], s[100:101] offset:16
	global_load_dwordx4 v[208:211], v151, s[98:99] offset:16
	s_waitcnt vmcnt(14)
	v_pk_fma_f32 v[68:69], v[68:69], v[180:181], v[212:213]
	v_pk_fma_f32 v[70:71], v[70:71], v[182:183], v[214:215]
	global_store_dwordx4 v149, v[68:71], s[100:101] offset:512
	global_load_dwordx4 v[212:215], v151, s[98:99] offset:512
	s_waitcnt vmcnt(14)
	v_pk_fma_f32 v[64:65], v[64:65], v[184:185], v[160:161]
	v_pk_fma_f32 v[66:67], v[66:67], v[186:187], v[162:163]
	global_store_dwordx4 v149, v[64:67], s[100:101] offset:528
	global_load_dwordx4 v[160:163], v151, s[98:99] offset:528
	s_waitcnt vmcnt(14)
	v_pk_fma_f32 v[60:61], v[60:61], v[172:173], v[188:189]
	v_pk_fma_f32 v[62:63], v[62:63], v[174:175], v[190:191]
	global_store_dwordx4 v150, v[60:63], s[100:101] offset:0
	global_load_dwordx4 v[188:191], v164, s[98:99] offset:0
	s_waitcnt vmcnt(14)
	v_pk_fma_f32 v[56:57], v[56:57], v[176:177], v[192:193]
	v_pk_fma_f32 v[58:59], v[58:59], v[178:179], v[194:195]
	global_store_dwordx4 v150, v[56:59], s[100:101] offset:16
	global_load_dwordx4 v[192:195], v164, s[98:99] offset:16
	s_waitcnt vmcnt(14)
	v_pk_fma_f32 v[52:53], v[52:53], v[180:181], v[196:197]
	v_pk_fma_f32 v[54:55], v[54:55], v[182:183], v[198:199]
	global_store_dwordx4 v150, v[52:55], s[100:101] offset:512
	global_load_dwordx4 v[196:199], v164, s[98:99] offset:512
	s_waitcnt vmcnt(14)
	v_pk_fma_f32 v[48:49], v[48:49], v[184:185], v[200:201]
	v_pk_fma_f32 v[50:51], v[50:51], v[186:187], v[202:203]
	global_store_dwordx4 v150, v[48:51], s[100:101] offset:528
	global_load_dwordx4 v[200:203], v164, s[98:99] offset:528
	s_waitcnt vmcnt(14)
	v_pk_fma_f32 v[44:45], v[44:45], v[172:173], v[204:205]
	v_pk_fma_f32 v[46:47], v[46:47], v[174:175], v[206:207]
	global_store_dwordx4 v151, v[44:47], s[100:101] offset:0
	global_load_dwordx4 v[204:207], v165, s[98:99] offset:0
	s_waitcnt vmcnt(14)
	v_pk_fma_f32 v[40:41], v[40:41], v[176:177], v[208:209]
	v_pk_fma_f32 v[42:43], v[42:43], v[178:179], v[210:211]
	global_store_dwordx4 v151, v[40:43], s[100:101] offset:16
	global_load_dwordx4 v[208:211], v165, s[98:99] offset:16
	s_waitcnt vmcnt(14)
	v_pk_fma_f32 v[36:37], v[36:37], v[180:181], v[212:213]
	v_pk_fma_f32 v[38:39], v[38:39], v[182:183], v[214:215]
	global_store_dwordx4 v151, v[36:39], s[100:101] offset:512
	global_load_dwordx4 v[212:215], v165, s[98:99] offset:512
	s_waitcnt vmcnt(14)
	v_pk_fma_f32 v[32:33], v[32:33], v[184:185], v[160:161]
	v_pk_fma_f32 v[34:35], v[34:35], v[186:187], v[162:163]
	global_store_dwordx4 v151, v[32:35], s[100:101] offset:528
	global_load_dwordx4 v[160:163], v165, s[98:99] offset:528
	s_waitcnt vmcnt(14)
	v_pk_fma_f32 v[28:29], v[28:29], v[172:173], v[188:189]
	v_pk_fma_f32 v[30:31], v[30:31], v[174:175], v[190:191]
	global_store_dwordx4 v164, v[28:31], s[100:101] offset:0
	s_waitcnt vmcnt(13)
	v_pk_fma_f32 v[24:25], v[24:25], v[176:177], v[192:193]
	v_pk_fma_f32 v[26:27], v[26:27], v[178:179], v[194:195]
	global_store_dwordx4 v164, v[24:27], s[100:101] offset:16
	s_waitcnt vmcnt(12)
	v_pk_fma_f32 v[20:21], v[20:21], v[180:181], v[196:197]
	v_pk_fma_f32 v[22:23], v[22:23], v[182:183], v[198:199]
	global_store_dwordx4 v164, v[20:23], s[100:101] offset:512
	s_waitcnt vmcnt(11)
	v_pk_fma_f32 v[16:17], v[16:17], v[184:185], v[200:201]
	v_pk_fma_f32 v[18:19], v[18:19], v[186:187], v[202:203]
	global_store_dwordx4 v164, v[16:19], s[100:101] offset:528
	s_waitcnt vmcnt(10)
	v_pk_fma_f32 v[12:13], v[12:13], v[172:173], v[204:205]
	v_pk_fma_f32 v[14:15], v[14:15], v[174:175], v[206:207]
	global_store_dwordx4 v165, v[12:15], s[100:101] offset:0
	s_waitcnt vmcnt(9)
	v_pk_fma_f32 v[8:9], v[8:9], v[176:177], v[208:209]
	v_pk_fma_f32 v[10:11], v[10:11], v[178:179], v[210:211]
	global_store_dwordx4 v165, v[8:11], s[100:101] offset:16
	s_waitcnt vmcnt(8)
	v_pk_fma_f32 v[4:5], v[4:5], v[180:181], v[212:213]
	v_pk_fma_f32 v[6:7], v[6:7], v[182:183], v[214:215]
	global_store_dwordx4 v165, v[4:7], s[100:101] offset:512
	s_waitcnt vmcnt(7)
	v_pk_fma_f32 v[0:1], v[0:1], v[184:185], v[160:161]
	v_pk_fma_f32 v[2:3], v[2:3], v[186:187], v[162:163]
	global_store_dwordx4 v165, v[0:3], s[100:101] offset:528
	s_andn2_b64 vcc, exec, s[4:5]
	s_mov_b64 s[4:5], -1
	s_cbranch_vccnz .LBB0_1668
	s_andn2_b64 vcc, exec, s[16:17]
	s_cbranch_vccnz .LBB0_1667
	s_barrier
	s_branch .LBB0_1667
